# dy2 + out-phase tiles handed out dynamically (per-XCD atomic counter, LDS broadcast)
# baseline (speedup 1.0000x reference)
; DI void out_phase(const Params& p, int l, char* smem, const bool dry = false) {
;     ...
;     float xo[4][4][4];
; #pragma unroll
;     for (int i = 0; i < 4; i++)
; #pragma unroll
;       for (int r = 0; r < 4; r++) {
;         const int tok = mt * 128 + wm * 64 + i * 16 + g4 * 4 + r;
;         const float* xr = xrow_ptr(p, l, tok);
; #pragma unroll
;         for (int jn = 0; jn < 4; jn++) xo[i][r][jn] = xr[nt * 128 + wn * 64 + jn * 16 + cl];
;       }
; #pragma unroll
;     for (int i = 0; i < 4; i++)
; #pragma unroll
;       for (int r = 0; r < 4; r++) {
;         const int tok = mt * 128 + wm * 64 + i * 16 + g4 * 4 + r;
; #pragma unroll
;         for (int jn = 0; jn < 4; jn++) {
;           const int n = nt * 128 + wn * 64 + jn * 16 + cl;
;           p.out[(size_t)tok * DM + n] = xo[i][r][jn] + acc[i][jn][r];
;         }
;       }
.LBB0_1737:
	v_cmp_eq_u32_e64 s[98:99], s58, v104
	v_cmp_eq_u32_e64 s[100:101], s86, v104
	s_nop 1
	v_cndmask_b32_e64 v104, v224, v222, s[100:101]
	v_cndmask_b32_e64 v105, v225, v223, s[100:101]
	v_cndmask_b32_e64 v104, v104, v220, s[98:99]
	v_cndmask_b32_e64 v105, v105, v221, s[98:99]
	s_waitcnt vmcnt(0)
	s_load_dwordx2 s[4:5], s[0:1], 0xe8
	v_lshlrev_b64 v[102:103], 12, v[102:103]
	v_add_f32_e32 v111, v52, v111
	v_add_f32_e32 v110, v56, v110
	v_add_f32_e32 v60, v60, v109
	v_add_f32_e32 v64, v64, v108
	v_add_f32_e32 v108, v53, v115
	v_add_f32_e32 v109, v57, v114
	v_lshlrev_b64 v[52:53], 12, v[74:75]
	v_add_f32_e32 v75, v58, v118
	v_lshlrev_b64 v[56:57], 12, v[76:77]
	v_add_f32_e32 v77, v59, v122
	v_lshlrev_b64 v[58:59], 12, v[80:81]
	v_lshlrev_b64 v[72:73], 2, v[72:73]
	v_add_f32_e32 v74, v54, v119
	v_add_f32_e32 v76, v55, v123
	v_lshlrev_b64 v[54:55], 12, v[78:79]
	v_add_f32_e32 v78, v48, v127
	v_add_f32_e32 v80, v49, v131
	s_waitcnt lgkmcnt(0)
	v_lshl_add_u64 v[48:49], s[4:5], 0, v[52:53]
	v_lshl_add_u64 v[52:53], s[4:5], 0, v[56:57]
	v_lshl_add_u64 v[56:57], s[4:5], 0, v[58:59]
	v_lshlrev_b64 v[68:69], 12, v[68:69]
	v_lshlrev_b64 v[70:71], 12, v[70:71]
	v_add_f32_e32 v65, v65, v112
	v_add_f32_e32 v79, v44, v126
	v_add_f32_e32 v112, v40, v125
	v_add_f32_e32 v81, v45, v130
	v_add_f32_e32 v114, v41, v129
	v_lshl_add_u64 v[40:41], s[4:5], 0, v[68:69]
	v_lshl_add_u64 v[44:45], s[4:5], 0, v[70:71]
	v_add_f32_e32 v61, v61, v113
	v_add_f32_e32 v113, v36, v124
	v_add_f32_e32 v115, v37, v128
	v_lshlrev_b64 v[36:37], 12, v[82:83]
	v_lshl_add_u64 v[54:55], s[4:5], 0, v[54:55]
	v_lshl_add_u64 v[36:37], s[4:5], 0, v[36:37]
	v_lshl_add_u64 v[40:41], v[40:41], 0, v[72:73]
	v_add_f32_e32 v62, v62, v117
	v_add_f32_e32 v66, v66, v116
	v_add_f32_e32 v63, v63, v121
	v_add_f32_e32 v67, v67, v120
	v_add_f32_e32 v50, v50, v135
	v_add_f32_e32 v46, v46, v134
	v_lshl_add_u64 v[44:45], v[44:45], 0, v[72:73]
	v_lshl_add_u64 v[48:49], v[48:49], 0, v[72:73]
	v_lshl_add_u64 v[52:53], v[52:53], 0, v[72:73]
	v_lshl_add_u64 v[54:55], v[54:55], 0, v[72:73]
	v_lshl_add_u64 v[56:57], v[56:57], 0, v[72:73]
	v_lshl_add_u64 v[36:37], v[36:37], 0, v[72:73]
	v_add_f32_e32 v38, v38, v132
	v_add_f32_e32 v16, v16, v143
	v_add_f32_e32 v12, v12, v142
	v_add_f32_e32 v8, v8, v141
	v_add_f32_e32 v4, v4, v140
	v_add_f32_e32 v6, v6, v148
	s_waitcnt vmcnt(0)
; DI void out_phase(const Params& p, int l, char* smem, const bool dry = false) {
;     ...
;   for (int e = slot;; e += slots) {
;     int mt, nt;
;     if (!xcd_tile(e, 8, mt, nt)) break;
;     ...
;         for (int jn = 0; jn < 4; jn++) {
;           const int n = nt * 128 + wn * 64 + jn * 16 + cl;
;           p.out[(size_t)tok * DM + n] = xo[i][r][jn] + acc[i][jn][r];
;         }
;       }
	v_lshl_add_u64 v[58:59], v[104:105], 0, v[102:103]
	v_lshl_add_u64 v[58:59], v[58:59], 0, v[72:73]
	global_load_dword v68, v[58:59], off
	global_load_dword v69, v[58:59], off offset:64
	global_load_dword v70, v[58:59], off offset:128
	s_nop 0
	global_load_dword v58, v[58:59], off offset:192
	s_nop 0
	global_store_dword v[40:41], v111, off
	global_store_dword v[40:41], v110, off offset:64
	global_store_dword v[40:41], v60, off offset:128
	global_store_dword v[40:41], v64, off offset:192
	global_store_dword v[44:45], v108, off
	global_store_dword v[44:45], v109, off offset:64
	global_store_dword v[44:45], v61, off offset:128
	global_store_dword v[44:45], v65, off offset:192
	global_store_dword v[48:49], v74, off
	global_store_dword v[48:49], v75, off offset:64
	global_store_dword v[48:49], v62, off offset:128
	global_store_dword v[48:49], v66, off offset:192
	global_store_dword v[52:53], v76, off
	global_store_dword v[52:53], v77, off offset:64
	global_store_dword v[52:53], v63, off offset:128
	global_store_dword v[52:53], v67, off offset:192
	global_store_dword v[54:55], v78, off
	global_store_dword v[54:55], v79, off offset:64
	global_store_dword v[54:55], v112, off offset:128
	global_store_dword v[54:55], v113, off offset:192
	global_store_dword v[56:57], v80, off
	global_store_dword v[56:57], v81, off offset:64
	global_store_dword v[56:57], v114, off offset:128
	global_store_dword v[56:57], v115, off offset:192
	global_store_dword v[36:37], v50, off
	global_store_dword v[36:37], v46, off offset:64
	v_add_f32_e32 v40, v42, v133
	global_store_dword v[36:37], v40, off offset:128
	global_store_dword v[36:37], v38, off offset:192
	v_lshlrev_b64 v[36:37], 12, v[84:85]
	v_lshl_add_u64 v[36:37], s[4:5], 0, v[36:37]
	v_add_f32_e32 v38, v51, v139
	v_lshl_add_u64 v[36:37], v[36:37], 0, v[72:73]
	global_store_dword v[36:37], v38, off
	v_add_f32_e32 v38, v47, v138
	global_store_dword v[36:37], v38, off offset:64
	v_add_f32_e32 v38, v43, v137
	global_store_dword v[36:37], v38, off offset:128
	v_add_f32_e32 v38, v39, v136
	global_store_dword v[36:37], v38, off offset:192
	v_lshlrev_b64 v[36:37], 12, v[86:87]
	v_lshl_add_u64 v[36:37], s[4:5], 0, v[36:37]
	v_lshl_add_u64 v[36:37], v[36:37], 0, v[72:73]
	global_store_dword v[36:37], v16, off
	global_store_dword v[36:37], v12, off offset:64
	global_store_dword v[36:37], v8, off offset:128
	global_store_dword v[36:37], v4, off offset:192
	v_lshlrev_b64 v[36:37], 12, v[88:89]
	v_lshl_add_u64 v[36:37], s[4:5], 0, v[36:37]
	v_add_f32_e32 v4, v17, v147
	v_lshl_add_u64 v[16:17], v[36:37], 0, v[72:73]
	global_store_dword v[16:17], v4, off
	v_add_f32_e32 v4, v13, v146
	global_store_dword v[16:17], v4, off offset:64
	v_add_f32_e32 v4, v9, v145
	global_store_dword v[16:17], v4, off offset:128
	v_add_f32_e32 v4, v5, v144
	global_store_dword v[16:17], v4, off offset:192
	v_lshlrev_b64 v[4:5], 12, v[90:91]
	v_lshl_add_u64 v[4:5], s[4:5], 0, v[4:5]
	v_add_f32_e32 v8, v18, v151
	v_lshl_add_u64 v[4:5], v[4:5], 0, v[72:73]
	global_store_dword v[4:5], v8, off
	v_add_f32_e32 v8, v14, v150
	global_store_dword v[4:5], v8, off offset:64
	v_add_f32_e32 v8, v10, v149
	global_store_dword v[4:5], v8, off offset:128
	global_store_dword v[4:5], v6, off offset:192
	v_lshlrev_b64 v[4:5], 12, v[92:93]
	v_lshl_add_u64 v[4:5], s[4:5], 0, v[4:5]
	v_add_f32_e32 v6, v19, v155
	v_lshl_add_u64 v[4:5], v[4:5], 0, v[72:73]
	global_store_dword v[4:5], v6, off
	v_add_f32_e32 v6, v15, v154
	global_store_dword v[4:5], v6, off offset:64
	v_add_f32_e32 v6, v11, v153
	global_store_dword v[4:5], v6, off offset:128
	v_add_f32_e32 v6, v7, v152
	global_store_dword v[4:5], v6, off offset:192
	v_lshlrev_b64 v[4:5], 12, v[94:95]
	v_lshl_add_u64 v[4:5], s[4:5], 0, v[4:5]
	v_add_f32_e32 v6, v20, v159
	v_lshl_add_u64 v[4:5], v[4:5], 0, v[72:73]
	global_store_dword v[4:5], v6, off
	v_add_f32_e32 v6, v24, v158
	global_store_dword v[4:5], v6, off offset:64
	v_add_f32_e32 v6, v28, v157
	global_store_dword v[4:5], v6, off offset:128
	v_add_f32_e32 v6, v32, v156
	global_store_dword v[4:5], v6, off offset:192
	v_lshlrev_b64 v[4:5], 12, v[96:97]
	v_lshl_add_u64 v[4:5], s[4:5], 0, v[4:5]
	v_add_f32_e32 v6, v21, v163
	v_lshl_add_u64 v[4:5], v[4:5], 0, v[72:73]
	global_store_dword v[4:5], v6, off
	v_add_f32_e32 v6, v25, v162
	global_store_dword v[4:5], v6, off offset:64
	v_add_f32_e32 v6, v29, v161
	global_store_dword v[4:5], v6, off offset:128
	v_add_f32_e32 v6, v33, v160
	global_store_dword v[4:5], v6, off offset:192
	v_lshlrev_b64 v[4:5], 12, v[98:99]
	v_lshl_add_u64 v[4:5], s[4:5], 0, v[4:5]
	v_add_f32_e32 v6, v22, v170
	v_lshl_add_u64 v[4:5], v[4:5], 0, v[72:73]
	global_store_dword v[4:5], v6, off
	v_add_f32_e32 v6, v26, v169
	global_store_dword v[4:5], v6, off offset:64
	v_add_f32_e32 v6, v30, v168
	global_store_dword v[4:5], v6, off offset:128
	v_add_f32_e32 v6, v34, v165
	global_store_dword v[4:5], v6, off offset:192
	v_lshlrev_b64 v[4:5], 12, v[100:101]
	v_lshl_add_u64 v[4:5], s[4:5], 0, v[4:5]
	s_waitcnt vmcnt(62)
	v_add_f32_e32 v6, v23, v68
	v_lshl_add_u64 v[4:5], v[4:5], 0, v[72:73]
	global_store_dword v[4:5], v6, off
	v_add_f32_e32 v6, v27, v69
	global_store_dword v[4:5], v6, off offset:64
	s_waitcnt vmcnt(62)
	v_add_f32_e32 v6, v31, v70
	global_store_dword v[4:5], v6, off offset:128
	v_add_f32_e32 v6, v35, v58
	global_store_dword v[4:5], v6, off offset:192
	v_lshrrev_b32_e32 v253, 6, v182
	v_readlane_b32 s98, v254, 16
	v_readlane_b32 s99, v254, 17
	v_readfirstlane_b32 s4, v253
	v_readlane_b32 s100, v254, 0
	v_readlane_b32 s101, v254, 51
	s_nop 1
	s_cmp_lg_u32 s4, 0
	s_cbranch_scc1 .Ldyno_wait
	s_and_b32 s100, s100, 7
	s_lshl_b32 s100, s100, 8
	s_lshl_b32 s101, s101, 2
	s_add_u32 s100, s100, s101
	s_add_u32 s100, s100, 0x108
	s_add_u32 s98, s98, s100
	s_addc_u32 s99, s99, 0
	s_mov_b64 s[100:101], exec
	s_mov_b64 exec, 1
	s_nop 1
	v_mov_b32_e32 v252, 1
	global_atomic_add v253, v164, v252, s[98:99] sc0
	v_mov_b32_e32 v251, 0x11ff0
	s_waitcnt vmcnt(0)
	ds_write_b32 v251, v253
	s_mov_b64 exec, s[100:101]
.Ldyno_wait:
	s_waitcnt lgkmcnt(0)
	s_barrier
	v_mov_b32_e32 v251, 0x11ff0
	ds_read_b32 v253, v251
	s_waitcnt lgkmcnt(0)
	v_readfirstlane_b32 s17, v253
	s_nop 0
	s_add_i32 s17, s17, 64
	s_cmpk_lt_u32 s17, 0x90
	s_cbranch_scc0 .LBB0_1867
